# cvt phase: 8 row-strided loads in flight per lane with counted vmcnt (on top of conv next-channel prefetch)
# speedup vs baseline: 1.0112x; 1.0003x over previous
; DI unsigned pack2(float a, float b) { f32x2_t v = {a, b}; return __builtin_bit_cast(unsigned, __builtin_convertvector(v, bf16x2_t)); }
; DI void cvt_phase(int wvs, const float* __restrict__ x, bf16_t* HB) {
;   const int tid = opaque_tid(wvs);
;   const size_t n4 = (size_t)MTOT * 1024 / 4;
;   for (size_t i = (size_t)blockIdx.x * NT + tid; i < n4; i += (size_t)gridDim.x * NT) {
;     const float4 v = *(const float4*)(x + i * 4);
;     uint2 pk; pk.x = pack2(v.x, v.y); pk.y = pack2(v.z, v.w);
;     *(uint2*)(HB + i * 4) = pk;
;   }
.LBB0_7:
	global_load_dwordx4 v[8:11], v[6:7], off offset:-8
	v_lshl_add_u64 v[6:7], v[6:7], 0, s[4:5]
	global_load_dwordx4 v[12:15], v[6:7], off offset:-8
	v_lshl_add_u64 v[6:7], v[6:7], 0, s[4:5]
	global_load_dwordx4 v[16:19], v[6:7], off offset:-8
	v_lshl_add_u64 v[6:7], v[6:7], 0, s[4:5]
	global_load_dwordx4 v[20:23], v[6:7], off offset:-8
	v_lshl_add_u64 v[6:7], v[6:7], 0, s[4:5]
	global_load_dwordx4 v[24:27], v[6:7], off offset:-8
	v_lshl_add_u64 v[6:7], v[6:7], 0, s[4:5]
	global_load_dwordx4 v[28:31], v[6:7], off offset:-8
	v_lshl_add_u64 v[6:7], v[6:7], 0, s[4:5]
	global_load_dwordx4 v[32:35], v[6:7], off offset:-8
	v_lshl_add_u64 v[6:7], v[6:7], 0, s[4:5]
	global_load_dwordx4 v[36:39], v[6:7], off offset:-8
	v_lshl_add_u64 v[6:7], v[6:7], 0, s[4:5]
	v_lshl_add_u64 v[2:3], v[2:3], 0, s[24:25]
	v_lshl_add_u64 v[2:3], v[2:3], 0, s[24:25]
	v_lshl_add_u64 v[2:3], v[2:3], 0, s[24:25]
	v_lshl_add_u64 v[2:3], v[2:3], 0, s[24:25]
	v_lshl_add_u64 v[2:3], v[2:3], 0, s[24:25]
	v_lshl_add_u64 v[2:3], v[2:3], 0, s[24:25]
	v_lshl_add_u64 v[2:3], v[2:3], 0, s[24:25]
	v_lshl_add_u64 v[2:3], v[2:3], 0, s[24:25]
	v_cmp_lt_u64_e32 vcc, s[8:9], v[2:3]
	s_or_b64 s[6:7], vcc, s[6:7]
	s_waitcnt vmcnt(7)
	v_cvt_pk_bf16_f32 v8, v8, v9
	v_cvt_pk_bf16_f32 v9, v10, v11
	global_store_dwordx2 v[4:5], v[8:9], off offset:-4
	v_lshl_add_u64 v[4:5], v[4:5], 0, s[2:3]
	s_waitcnt vmcnt(7)
	v_cvt_pk_bf16_f32 v12, v12, v13
	v_cvt_pk_bf16_f32 v13, v14, v15
	global_store_dwordx2 v[4:5], v[12:13], off offset:-4
	v_lshl_add_u64 v[4:5], v[4:5], 0, s[2:3]
	s_waitcnt vmcnt(7)
	v_cvt_pk_bf16_f32 v16, v16, v17
	v_cvt_pk_bf16_f32 v17, v18, v19
	global_store_dwordx2 v[4:5], v[16:17], off offset:-4
	v_lshl_add_u64 v[4:5], v[4:5], 0, s[2:3]
	s_waitcnt vmcnt(7)
	v_cvt_pk_bf16_f32 v20, v20, v21
	v_cvt_pk_bf16_f32 v21, v22, v23
	global_store_dwordx2 v[4:5], v[20:21], off offset:-4
	v_lshl_add_u64 v[4:5], v[4:5], 0, s[2:3]
	s_waitcnt vmcnt(7)
	v_cvt_pk_bf16_f32 v24, v24, v25
	v_cvt_pk_bf16_f32 v25, v26, v27
	global_store_dwordx2 v[4:5], v[24:25], off offset:-4
	v_lshl_add_u64 v[4:5], v[4:5], 0, s[2:3]
	s_waitcnt vmcnt(7)
	v_cvt_pk_bf16_f32 v28, v28, v29
	v_cvt_pk_bf16_f32 v29, v30, v31
	global_store_dwordx2 v[4:5], v[28:29], off offset:-4
	v_lshl_add_u64 v[4:5], v[4:5], 0, s[2:3]
	s_waitcnt vmcnt(7)
	v_cvt_pk_bf16_f32 v32, v32, v33
	v_cvt_pk_bf16_f32 v33, v34, v35
	global_store_dwordx2 v[4:5], v[32:33], off offset:-4
	v_lshl_add_u64 v[4:5], v[4:5], 0, s[2:3]
	s_waitcnt vmcnt(7)
	v_cvt_pk_bf16_f32 v36, v36, v37
	v_cvt_pk_bf16_f32 v37, v38, v39
	global_store_dwordx2 v[4:5], v[36:37], off offset:-4
	v_lshl_add_u64 v[4:5], v[4:5], 0, s[2:3]
	s_andn2_b64 exec, exec, s[6:7]
	s_cbranch_execnz .LBB0_7
